# e40: e33+e14 + barrier leaders drop the dead per-XCD generation bump and the acknowledgement waits before leaving the barrier
# speedup vs baseline: 1.0096x; 1.0049x over previous
; __device__ __forceinline__ unsigned xb_ld(unsigned* p)              { return __hip_atomic_load(p, __ATOMIC_RELAXED, __HIP_MEMORY_SCOPE_AGENT); }
; __device__ __forceinline__ unsigned xb_add(unsigned* p, unsigned v) { return __hip_atomic_fetch_add(p, v, __ATOMIC_RELAXED, __HIP_MEMORY_SCOPE_AGENT); }
; #define XB_SPIN(cond, bar) do { unsigned _sp = 0; while (cond) { __builtin_amdgcn_s_sleep(1); \
;     if ((++_sp & 255u) == 0u) { if (xb_ld(&(bar)[XB_TMO])) break; if (_sp > XB_SPIN_CAP) { atomicAdd(&(bar)[XB_TMO], 1u); break; } } } } while (0)
; __device__ __forceinline__ void xcd_barrier(const XcdBarrier& b) {
;     ...
;             if (og + 1u == (tg + 1u) * nx) xb_add(&bar[XB_TOPGEN], 1u);
;             else XB_SPIN(xb_ld(&bar[XB_TOPGEN]) == tg, bar);
;             __builtin_amdgcn_fence(__ATOMIC_ACQUIRE, "agent");
;             xb_add(&bar[XB_XGEN(b.x)], 1u);
;             asm volatile("s_waitcnt vmcnt(0)" ::: "memory");
.LBB0_128:
	s_or_b64 exec, exec, s[8:9]
	s_mov_b64 s[8:9], exec
	v_mbcnt_lo_u32_b32 v1, s8, 0
	v_mbcnt_hi_u32_b32 v1, s9, v1
	v_cmp_eq_u32_e32 vcc, 0, v1
	buffer_inv sc1
	s_and_saveexec_b64 s[10:11], vcc
	s_cbranch_execz .LBB0_130
	s_bcnt1_i32_b64 s0, s[8:9]
	v_mov_b32_e32 v1, 0x2000
	v_mov_b32_e32 v2, s0
.LBB0_130:
	s_or_b64 exec, exec, s[10:11]
.LBB0_131:
	s_or_b64 exec, exec, s[2:3]
	s_waitcnt lgkmcnt(0)
	s_barrier

; __device__ __forceinline__ unsigned xb_ld(unsigned* p)              { return __hip_atomic_load(p, __ATOMIC_RELAXED, __HIP_MEMORY_SCOPE_AGENT); }
; __device__ __forceinline__ unsigned xb_add(unsigned* p, unsigned v) { return __hip_atomic_fetch_add(p, v, __ATOMIC_RELAXED, __HIP_MEMORY_SCOPE_AGENT); }
; #define XB_SPIN(cond, bar) do { unsigned _sp = 0; while (cond) { __builtin_amdgcn_s_sleep(1); \
;     if ((++_sp & 255u) == 0u) { if (xb_ld(&(bar)[XB_TMO])) break; if (_sp > XB_SPIN_CAP) { atomicAdd(&(bar)[XB_TMO], 1u); break; } } } } while (0)
; __device__ __forceinline__ void xcd_barrier(const XcdBarrier& b) {
;     ...
;             const unsigned og = xb_add(&bar[XB_TOP], 1u);
;             const unsigned tg = og / nx;
;             if (og + 1u == (tg + 1u) * nx) xb_add(&bar[XB_TOPGEN], 1u);
;             else XB_SPIN(xb_ld(&bar[XB_TOPGEN]) == tg, bar);
;             __builtin_amdgcn_fence(__ATOMIC_ACQUIRE, "agent");
;             xb_add(&bar[XB_XGEN(b.x)], 1u);
;             asm volatile("s_waitcnt vmcnt(0)" ::: "memory");
;         } else {
;             XB_SPIN(xb_ld(&bar[XB_XGEN(b.x)]) == gen, bar);
;             __builtin_amdgcn_fence(__ATOMIC_ACQUIRE, "agent");
;             asm volatile("s_waitcnt vmcnt(0)" ::: "memory");
;         }
;     }
;     __syncthreads();
.LBB0_282:
	s_or_b64 exec, exec, s[10:11]
.LBB0_283:
	s_or_b64 exec, exec, s[4:5]
	s_waitcnt lgkmcnt(0)
	s_barrier

; __device__ __forceinline__ unsigned xb_ld(unsigned* p)              { return __hip_atomic_load(p, __ATOMIC_RELAXED, __HIP_MEMORY_SCOPE_AGENT); }
; __device__ __forceinline__ unsigned xb_add(unsigned* p, unsigned v) { return __hip_atomic_fetch_add(p, v, __ATOMIC_RELAXED, __HIP_MEMORY_SCOPE_AGENT); }
; #define XB_SPIN(cond, bar) do { unsigned _sp = 0; while (cond) { __builtin_amdgcn_s_sleep(1); \
;     if ((++_sp & 255u) == 0u) { if (xb_ld(&(bar)[XB_TMO])) break; if (_sp > XB_SPIN_CAP) { atomicAdd(&(bar)[XB_TMO], 1u); break; } } } } while (0)
; __device__ __forceinline__ void xcd_barrier(const XcdBarrier& b) {
;     ...
;             const unsigned og = xb_add(&bar[XB_TOP], 1u);
;             const unsigned tg = og / nx;
;             if (og + 1u == (tg + 1u) * nx) xb_add(&bar[XB_TOPGEN], 1u);
;             else XB_SPIN(xb_ld(&bar[XB_TOPGEN]) == tg, bar);
;             __builtin_amdgcn_fence(__ATOMIC_ACQUIRE, "agent");
;             xb_add(&bar[XB_XGEN(b.x)], 1u);
;             asm volatile("s_waitcnt vmcnt(0)" ::: "memory");
;         } else {
;             XB_SPIN(xb_ld(&bar[XB_XGEN(b.x)]) == gen, bar);
;             __builtin_amdgcn_fence(__ATOMIC_ACQUIRE, "agent");
;             asm volatile("s_waitcnt vmcnt(0)" ::: "memory");
;         }
;     }
;     __syncthreads();
.LBB0_488:
	s_or_b64 exec, exec, s[10:11]
.LBB0_489:
	s_or_b64 exec, exec, s[4:5]
	s_waitcnt lgkmcnt(0)
	s_barrier

; __device__ __forceinline__ unsigned xb_ld(unsigned* p)              { return __hip_atomic_load(p, __ATOMIC_RELAXED, __HIP_MEMORY_SCOPE_AGENT); }
; __device__ __forceinline__ unsigned xb_add(unsigned* p, unsigned v) { return __hip_atomic_fetch_add(p, v, __ATOMIC_RELAXED, __HIP_MEMORY_SCOPE_AGENT); }
; #define XB_SPIN(cond, bar) do { unsigned _sp = 0; while (cond) { __builtin_amdgcn_s_sleep(1); \
;     if ((++_sp & 255u) == 0u) { if (xb_ld(&(bar)[XB_TMO])) break; if (_sp > XB_SPIN_CAP) { atomicAdd(&(bar)[XB_TMO], 1u); break; } } } } while (0)
; __device__ __forceinline__ void xcd_barrier(const XcdBarrier& b) {
;     ...
;             if (og + 1u == (tg + 1u) * nx) xb_add(&bar[XB_TOPGEN], 1u);
;             else XB_SPIN(xb_ld(&bar[XB_TOPGEN]) == tg, bar);
;             __builtin_amdgcn_fence(__ATOMIC_ACQUIRE, "agent");
;             xb_add(&bar[XB_XGEN(b.x)], 1u);
;             asm volatile("s_waitcnt vmcnt(0)" ::: "memory");
.LBB0_1047:
	s_or_b64 exec, exec, s[6:7]
	s_mov_b64 s[6:7], exec
	v_mbcnt_lo_u32_b32 v1, s6, 0
	v_mbcnt_hi_u32_b32 v1, s7, v1
	v_cmp_eq_u32_e32 vcc, 0, v1
	buffer_inv sc1
	s_and_saveexec_b64 s[8:9], vcc
	s_cbranch_execz .LBB0_1049
	s_bcnt1_i32_b64 s0, s[6:7]
	v_mov_b32_e32 v1, 0x2000
	v_mov_b32_e32 v2, s0
.LBB0_1049:
	s_or_b64 exec, exec, s[8:9]
.LBB0_1050:
	s_or_b64 exec, exec, s[2:3]
	s_waitcnt lgkmcnt(0)
	s_barrier

; __device__ __forceinline__ unsigned xb_ld(unsigned* p)              { return __hip_atomic_load(p, __ATOMIC_RELAXED, __HIP_MEMORY_SCOPE_AGENT); }
; __device__ __forceinline__ unsigned xb_add(unsigned* p, unsigned v) { return __hip_atomic_fetch_add(p, v, __ATOMIC_RELAXED, __HIP_MEMORY_SCOPE_AGENT); }
; #define XB_SPIN(cond, bar) do { unsigned _sp = 0; while (cond) { __builtin_amdgcn_s_sleep(1); \
;     if ((++_sp & 255u) == 0u) { if (xb_ld(&(bar)[XB_TMO])) break; if (_sp > XB_SPIN_CAP) { atomicAdd(&(bar)[XB_TMO], 1u); break; } } } } while (0)
; __device__ __forceinline__ void xcd_barrier(const XcdBarrier& b) {
;     ...
;             const unsigned og = xb_add(&bar[XB_TOP], 1u);
;             const unsigned tg = og / nx;
;             if (og + 1u == (tg + 1u) * nx) xb_add(&bar[XB_TOPGEN], 1u);
;             else XB_SPIN(xb_ld(&bar[XB_TOPGEN]) == tg, bar);
;             __builtin_amdgcn_fence(__ATOMIC_ACQUIRE, "agent");
;             xb_add(&bar[XB_XGEN(b.x)], 1u);
;             asm volatile("s_waitcnt vmcnt(0)" ::: "memory");
;         } else {
;             XB_SPIN(xb_ld(&bar[XB_XGEN(b.x)]) == gen, bar);
;             __builtin_amdgcn_fence(__ATOMIC_ACQUIRE, "agent");
;             asm volatile("s_waitcnt vmcnt(0)" ::: "memory");
;         }
;     }
;     __syncthreads();
.LBB0_1129:
	s_or_b64 exec, exec, s[10:11]
.LBB0_1130:
	s_or_b64 exec, exec, s[4:5]
	s_waitcnt lgkmcnt(0)
	s_barrier
